# v10 + convgate: the four A-row loads of a trip are issued at the top of the trip, ahead of the guarded G-row prefetch address code (first output wait becomes vmcnt(0))
# speedup vs baseline: 1.0065x; 1.0065x over previous
.LBB0_1327:
	s_add_i32 s90, s40, 2
	s_cmpk_lt_i32 s40, 0x17e
	s_cselect_b64 s[4:5], -1, 0
	s_add_i32 s31, s40, 1
	s_cmp_ge_i32 s31, s77
	s_cselect_b64 s[28:29], -1, 0
	s_cmp_lt_i32 s31, s77
	s_cselect_b64 s[8:9], -1, 0
	s_and_b64 s[4:5], s[4:5], s[8:9]
	v_cndmask_b32_e64 v100, 0, 1, s[4:5]
	v_cmp_ne_u32_e64 s[74:75], 1, v100
	s_andn2_b64 vcc, exec, s[4:5]
	v_add_u32_e32 v100, -3, v182
	v_mad_i64_i32 v[100:101], s[4:5], s35, v100, 0
	v_lshl_add_u64 v[124:125], v[100:101], 1, v[116:117]
	v_add_u32_e32 v100, -2, v182
	v_mad_i64_i32 v[100:101], s[4:5], s35, v100, 0
	v_lshl_add_u64 v[122:123], v[100:101], 1, v[116:117]
	v_add_u32_e32 v100, -1, v182
	v_mad_i64_i32 v[100:101], s[4:5], s35, v100, 0
	v_lshl_add_u64 v[120:121], v[100:101], 1, v[116:117]
	v_mad_i64_i32 v[100:101], s[4:5], s35, v182, 0
	global_load_dwordx4 v[112:115], v[124:125], off nt
	global_load_dwordx4 v[108:111], v[122:123], off nt
	v_lshl_add_u64 v[118:119], v[100:101], 1, v[116:117]
	global_load_dwordx4 v[104:107], v[120:121], off nt
	global_load_dwordx4 v[100:103], v[118:119], off nt
	s_cbranch_vccnz .LBB0_1339
	s_cmpk_lt_i32 s40, 0x7e
	s_cselect_b64 vcc, -1, 0
	s_and_b32 s4, s90, 3
	s_cmp_lg_u32 s4, 0
	s_cselect_b64 s[8:9], -1, 0
	s_cmp_lg_u32 s4, 3
	s_cselect_b64 s[92:93], -1, 0
	s_or_b64 s[78:79], s[46:47], s[8:9]
	s_or_b64 s[94:95], s[48:49], s[92:93]
	s_and_b64 s[78:79], s[78:79], s[94:95]
	v_cndmask_b32_e64 v80, 0, 1, s[44:45]
	v_cndmask_b32_e64 v81, 0, 1, s[78:79]
	v_cndmask_b32_e32 v80, v80, v81, vcc
	s_ashr_i32 s91, s90, 31
	v_and_b32_e32 v80, 1, v80
	s_lshl_b64 s[4:5], s[90:91], 6
	v_cmp_eq_u32_e64 s[78:79], 1, v80
	v_mov_b32_e32 v84, 0
	v_mov_b32_e32 v80, 0
	v_mov_b32_e32 v81, 0
	v_mov_b32_e32 v82, 0
	v_mov_b32_e32 v83, 0
	s_and_saveexec_b64 s[94:95], s[78:79]
	s_cbranch_execz .LBB0_1330
	v_lshl_add_u64 v[80:81], s[4:5], 0, v[140:141]
	v_mad_u64_u32 v[82:83], s[78:79], v80, s35, 0
	v_mad_i32_i24 v83, v81, s35, v83
	v_lshl_add_u64 v[80:81], v[82:83], 1, v[142:143]
	global_load_dwordx4 v[80:83], v[80:81], off nt

.LBB0_1339:
	s_cmpk_lt_i32 s40, 0x80
	s_cselect_b64 s[78:79], -1, 0
	s_and_b32 s4, s40, 63
	s_cmp_eq_u32 s4, 0
	s_cselect_b64 s[8:9], -1, 0
	s_or_b64 s[8:9], s[78:79], s[8:9]
	s_and_b64 vcc, exec, s[8:9]
	v_mov_b32_e32 v154, v74
	v_mov_b32_e32 v155, v75
	v_mov_b32_e32 v156, v72
	v_mov_b32_e32 v157, v73
	v_mov_b32_e32 v158, v78
	v_mov_b32_e32 v159, v79
	v_mov_b32_e32 v160, v76
	v_mov_b32_e32 v161, v77
	v_mov_b32_e32 v126, v74
	v_mov_b32_e32 v127, v75
	v_mov_b32_e32 v128, v72
	v_mov_b32_e32 v129, v73
	v_mov_b32_e32 v130, v78
	v_mov_b32_e32 v131, v79
	v_mov_b32_e32 v132, v76
	v_mov_b32_e32 v133, v77
	v_mov_b32_e32 v134, v74
	v_mov_b32_e32 v135, v75
	v_mov_b32_e32 v136, v72
	v_mov_b32_e32 v137, v73
	v_mov_b32_e32 v138, v78
	v_mov_b32_e32 v139, v79
	v_mov_b32_e32 v152, v76
	v_mov_b32_e32 v153, v77
	v_mov_b32_e32 v162, v74
	v_mov_b32_e32 v163, v75
	v_mov_b32_e32 v164, v72
	v_mov_b32_e32 v165, v73
	v_mov_b32_e32 v166, v78
	v_mov_b32_e32 v167, v79
	v_mov_b32_e32 v168, v76
	v_mov_b32_e32 v169, v77
	s_cbranch_vccnz .LBB0_1341
	s_mul_hi_u32 s5, s41, 0xaaaaaaab
	s_lshr_b32 s5, s5, 1
	s_mul_i32 s5, s5, 0xfffe7400
	v_add_u32_e32 v228, s5, v183
	ds_read_b128 v[130:133], v228
	ds_read_b128 v[134:137], v228 offset:512
	s_waitcnt lgkmcnt(1)
	v_lshlrev_b32_e32 v126, 16, v130
	s_waitcnt lgkmcnt(0)
	v_lshlrev_b32_e32 v138, 16, v134
	v_and_b32_e32 v139, 0xffff0000, v134
	v_lshlrev_b32_e32 v154, 16, v135
	v_and_b32_e32 v155, 0xffff0000, v135
	v_lshlrev_b32_e32 v158, 16, v136
	v_and_b32_e32 v159, 0xffff0000, v136
	v_lshlrev_b32_e32 v162, 16, v137
	v_and_b32_e32 v163, 0xffff0000, v137
	ds_read_b128 v[134:137], v228 offset:1024
	v_and_b32_e32 v127, 0xffff0000, v130
	v_lshlrev_b32_e32 v128, 16, v131
	v_and_b32_e32 v129, 0xffff0000, v131
	v_pk_fma_f32 v[126:127], v[4:5], v[126:127], v[76:77]
	v_pk_fma_f32 v[128:129], v[6:7], v[128:129], v[78:79]
	v_pk_fma_f32 v[152:153], v[4:5], v[138:139], v[76:77]
	v_pk_fma_f32 v[156:157], v[6:7], v[154:155], v[78:79]
	v_pk_fma_f32 v[138:139], v[8:9], v[138:139], v[126:127]
	v_pk_fma_f32 v[154:155], v[10:11], v[154:155], v[128:129]
	ds_read_b128 v[126:129], v228 offset:2048
	s_waitcnt lgkmcnt(1)
	v_lshlrev_b32_e32 v166, 16, v134
	v_and_b32_e32 v167, 0xffff0000, v134
	v_lshlrev_b32_e32 v184, 16, v135
	v_and_b32_e32 v185, 0xffff0000, v135
	v_lshlrev_b32_e32 v188, 16, v136
	v_and_b32_e32 v189, 0xffff0000, v136
	v_lshlrev_b32_e32 v192, 16, v137
	v_and_b32_e32 v193, 0xffff0000, v137
	ds_read_b128 v[134:137], v228 offset:1536
	v_lshlrev_b32_e32 v130, 16, v132
	v_and_b32_e32 v131, 0xffff0000, v132
	v_pk_fma_f32 v[130:131], v[0:1], v[130:131], v[72:73]
	v_pk_fma_f32 v[186:187], v[6:7], v[184:185], v[78:79]
	s_waitcnt lgkmcnt(0)
	v_lshlrev_b32_e32 v196, 16, v134
	v_and_b32_e32 v197, 0xffff0000, v134
	v_lshlrev_b32_e32 v134, 16, v135
	v_and_b32_e32 v135, 0xffff0000, v135
	v_pk_fma_f32 v[160:161], v[0:1], v[158:159], v[72:73]
	v_pk_fma_f32 v[164:165], v[2:3], v[162:163], v[74:75]
	v_pk_fma_f32 v[168:169], v[4:5], v[166:167], v[76:77]
	v_pk_fma_f32 v[130:131], v[12:13], v[158:159], v[130:131]
	v_pk_fma_f32 v[186:187], v[10:11], v[134:135], v[186:187]
	v_lshlrev_b32_e32 v220, 16, v126
	v_and_b32_e32 v221, 0xffff0000, v126
	v_lshlrev_b32_e32 v126, 16, v127
	v_and_b32_e32 v127, 0xffff0000, v127
	v_pk_fma_f32 v[152:153], v[8:9], v[166:167], v[152:153]
	v_pk_fma_f32 v[156:157], v[10:11], v[184:185], v[156:157]
	v_pk_fma_f32 v[158:159], v[12:13], v[188:189], v[160:161]
	v_pk_fma_f32 v[160:161], v[14:15], v[192:193], v[164:165]
	v_pk_fma_f32 v[218:219], v[8:9], v[196:197], v[168:169]
	v_pk_fma_f32 v[168:169], v[16:17], v[166:167], v[138:139]
	v_pk_fma_f32 v[166:167], v[18:19], v[184:185], v[154:155]
	v_pk_fma_f32 v[164:165], v[20:21], v[188:189], v[130:131]
	v_pk_fma_f32 v[130:131], v[18:19], v[126:127], v[186:187]
	ds_read_b128 v[184:187], v228 offset:2560
	v_pk_fma_f32 v[198:199], v[4:5], v[196:197], v[76:77]
	v_pk_fma_f32 v[200:201], v[6:7], v[134:135], v[78:79]
	v_lshlrev_b32_e32 v202, 16, v136
	v_and_b32_e32 v203, 0xffff0000, v136
	v_lshlrev_b32_e32 v216, 16, v137
	v_and_b32_e32 v217, 0xffff0000, v137
	v_pk_fma_f32 v[198:199], v[8:9], v[220:221], v[198:199]
	s_waitcnt lgkmcnt(0)
	v_lshlrev_b32_e32 v154, 16, v184
	v_and_b32_e32 v155, 0xffff0000, v184
	v_lshlrev_b32_e32 v132, 16, v133
	v_and_b32_e32 v133, 0xffff0000, v133
	v_pk_fma_f32 v[214:215], v[0:1], v[202:203], v[72:73]
	v_pk_fma_f32 v[136:137], v[2:3], v[216:217], v[74:75]
	v_pk_fma_f32 v[200:201], v[10:11], v[126:127], v[200:201]
	v_lshlrev_b32_e32 v222, 16, v128
	v_and_b32_e32 v223, 0xffff0000, v128
	v_lshlrev_b32_e32 v224, 16, v129
	v_and_b32_e32 v225, 0xffff0000, v129
	v_pk_fma_f32 v[138:139], v[18:19], v[134:135], v[156:157]
	v_pk_fma_f32 v[134:135], v[22:23], v[216:217], v[160:161]
	v_pk_fma_f32 v[160:161], v[16:17], v[154:155], v[198:199]
	v_lshlrev_b32_e32 v154, 16, v185
	v_and_b32_e32 v155, 0xffff0000, v185
	v_pk_fma_f32 v[132:133], v[2:3], v[132:133], v[74:75]
	v_pk_fma_f32 v[190:191], v[0:1], v[188:189], v[72:73]
	v_pk_fma_f32 v[194:195], v[2:3], v[192:193], v[74:75]
	v_pk_fma_f32 v[214:215], v[12:13], v[222:223], v[214:215]
	v_pk_fma_f32 v[226:227], v[14:15], v[224:225], v[136:137]
	v_pk_fma_f32 v[136:137], v[20:21], v[202:203], v[158:159]
	v_pk_fma_f32 v[158:159], v[18:19], v[154:155], v[200:201]
	v_lshlrev_b32_e32 v154, 16, v186
	v_and_b32_e32 v155, 0xffff0000, v186
	v_pk_fma_f32 v[132:133], v[14:15], v[162:163], v[132:133]
	v_pk_fma_f32 v[190:191], v[12:13], v[202:203], v[190:191]
	v_pk_fma_f32 v[194:195], v[14:15], v[216:217], v[194:195]
	v_pk_fma_f32 v[156:157], v[20:21], v[154:155], v[214:215]
	v_lshlrev_b32_e32 v154, 16, v187
	v_and_b32_e32 v155, 0xffff0000, v187
	v_pk_fma_f32 v[162:163], v[22:23], v[192:193], v[132:133]
	v_pk_fma_f32 v[152:153], v[16:17], v[196:197], v[152:153]
	v_pk_fma_f32 v[132:133], v[16:17], v[220:221], v[218:219]
	v_pk_fma_f32 v[128:129], v[20:21], v[222:223], v[190:191]
	v_pk_fma_f32 v[126:127], v[22:23], v[224:225], v[194:195]
	v_pk_fma_f32 v[154:155], v[22:23], v[154:155], v[226:227]

.LBB0_1343:
	s_waitcnt vmcnt(0)
	v_lshlrev_b32_e32 v184, 16, v112
	v_and_b32_e32 v185, 0xffff0000, v112
	v_lshlrev_b32_e32 v186, 16, v113
	v_and_b32_e32 v187, 0xffff0000, v113
	v_pk_mul_f32 v[112:113], v[168:169], v[168:169]
	v_lshlrev_b32_e32 v188, 16, v114
	v_fmamk_f32 v112, v112, 0xbdd2d3e8, v213
	v_mul_f32_e32 v112, v168, v112
	v_exp_f32_e32 v112, v112
	v_and_b32_e32 v114, 0xffff0000, v114
	v_lshlrev_b32_e32 v189, 16, v115
	v_and_b32_e32 v115, 0xffff0000, v115
	v_add_f32_e32 v112, 1.0, v112
	v_rcp_f32_e32 v112, v112
	s_and_b64 vcc, exec, s[74:75]
	s_mov_b32 s75, 0x800000
	v_mul_f32_e32 v112, v168, v112
	v_mul_f32_e32 v168, v112, v184
	v_fmamk_f32 v112, v113, 0xbdd2d3e8, v213
	v_mul_f32_e32 v112, v169, v112
	v_exp_f32_e32 v112, v112
	s_nop 0
	v_add_f32_e32 v112, 1.0, v112
	v_rcp_f32_e32 v112, v112
	s_nop 0
	v_mul_f32_e32 v112, v169, v112
	v_mul_f32_e32 v169, v112, v185
	v_pk_mul_f32 v[112:113], v[166:167], v[166:167]
	s_nop 0
	v_fmamk_f32 v112, v112, 0xbdd2d3e8, v213
	v_mul_f32_e32 v112, v166, v112
	v_exp_f32_e32 v112, v112
	s_nop 0
	v_add_f32_e32 v112, 1.0, v112
	v_rcp_f32_e32 v112, v112
	s_nop 0
	v_mul_f32_e32 v112, v166, v112
	v_mul_f32_e32 v166, v112, v186
	v_fmamk_f32 v112, v113, 0xbdd2d3e8, v213
	v_mul_f32_e32 v112, v167, v112
	v_exp_f32_e32 v112, v112
	s_nop 0
	v_add_f32_e32 v112, 1.0, v112
	v_rcp_f32_e32 v112, v112
	s_nop 0
	v_mul_f32_e32 v112, v167, v112
	v_mul_f32_e32 v167, v112, v187
	v_pk_mul_f32 v[112:113], v[164:165], v[164:165]
	s_nop 0
	v_fmamk_f32 v112, v112, 0xbdd2d3e8, v213
	v_mul_f32_e32 v112, v164, v112
	v_exp_f32_e32 v112, v112
	s_nop 0
	v_add_f32_e32 v112, 1.0, v112
	v_rcp_f32_e32 v112, v112
	s_nop 0
	v_mul_f32_e32 v112, v164, v112
	v_mul_f32_e32 v164, v112, v188
	v_fmamk_f32 v112, v113, 0xbdd2d3e8, v213
	v_mul_f32_e32 v112, v165, v112
	v_exp_f32_e32 v112, v112
	s_nop 0
	v_add_f32_e32 v112, 1.0, v112
	v_rcp_f32_e32 v112, v112
	s_nop 0
	v_mul_f32_e32 v112, v165, v112
	v_mul_f32_e32 v114, v112, v114
	v_pk_mul_f32 v[112:113], v[162:163], v[162:163]
	s_nop 0
	v_fmamk_f32 v112, v112, 0xbdd2d3e8, v213
	v_mul_f32_e32 v112, v162, v112
	v_exp_f32_e32 v112, v112
	s_nop 0
	v_add_f32_e32 v112, 1.0, v112
	v_rcp_f32_e32 v112, v112
	s_nop 0
	v_mul_f32_e32 v112, v162, v112
	v_mul_f32_e32 v162, v112, v189
	v_fmamk_f32 v112, v113, 0xbdd2d3e8, v213
	v_mul_f32_e32 v112, v163, v112
	v_exp_f32_e32 v112, v112
	s_nop 0
	v_add_f32_e32 v112, 1.0, v112
	v_rcp_f32_e32 v112, v112
	s_nop 0
	v_mul_f32_e32 v112, v163, v112
	v_mul_f32_e32 v115, v112, v115
	v_cvt_pk_bf16_f32 v112, v168, v169
	v_cvt_pk_bf16_f32 v113, v166, v167
	v_cvt_pk_bf16_f32 v114, v164, v114
	v_cvt_pk_bf16_f32 v115, v162, v115
	global_store_dwordx4 v[124:125], v[112:115], off
	s_waitcnt vmcnt(3)
	v_lshlrev_b32_e32 v124, 16, v110
	v_and_b32_e32 v110, 0xffff0000, v110
	v_lshlrev_b32_e32 v112, 16, v108
	v_and_b32_e32 v113, 0xffff0000, v108
	v_lshlrev_b32_e32 v114, 16, v109
	v_and_b32_e32 v115, 0xffff0000, v109
	v_pk_mul_f32 v[108:109], v[160:161], v[160:161]
	v_lshlrev_b32_e32 v125, 16, v111
	v_fmamk_f32 v108, v108, 0xbdd2d3e8, v213
	v_mul_f32_e32 v108, v160, v108
	v_exp_f32_e32 v108, v108
	v_and_b32_e32 v111, 0xffff0000, v111
	v_add_f32_e32 v108, 1.0, v108
	v_rcp_f32_e32 v108, v108
	s_nop 0
	v_mul_f32_e32 v108, v160, v108
	v_mul_f32_e32 v112, v108, v112
	v_fmamk_f32 v108, v109, 0xbdd2d3e8, v213
	v_mul_f32_e32 v108, v161, v108
	v_exp_f32_e32 v108, v108
	s_nop 0
	v_add_f32_e32 v108, 1.0, v108
	v_rcp_f32_e32 v108, v108
	s_nop 0
	v_mul_f32_e32 v108, v161, v108
	v_mul_f32_e32 v113, v108, v113
	v_pk_mul_f32 v[108:109], v[158:159], v[158:159]
	s_nop 0
	v_fmamk_f32 v108, v108, 0xbdd2d3e8, v213
	v_mul_f32_e32 v108, v158, v108
	v_exp_f32_e32 v108, v108
	s_nop 0
	v_add_f32_e32 v108, 1.0, v108
	v_rcp_f32_e32 v108, v108
	s_nop 0
	v_mul_f32_e32 v108, v158, v108
	v_mul_f32_e32 v114, v108, v114
	v_fmamk_f32 v108, v109, 0xbdd2d3e8, v213
	v_mul_f32_e32 v108, v159, v108
	v_exp_f32_e32 v108, v108
	s_nop 0
	v_add_f32_e32 v108, 1.0, v108
	v_rcp_f32_e32 v108, v108
	s_nop 0
	v_mul_f32_e32 v108, v159, v108
	v_mul_f32_e32 v115, v108, v115
	v_pk_mul_f32 v[108:109], v[156:157], v[156:157]
	s_nop 0
	v_fmamk_f32 v108, v108, 0xbdd2d3e8, v213
	v_mul_f32_e32 v108, v156, v108
	v_exp_f32_e32 v108, v108
	s_nop 0
	v_add_f32_e32 v108, 1.0, v108
	v_rcp_f32_e32 v108, v108
	s_nop 0
	v_mul_f32_e32 v108, v156, v108
	v_mul_f32_e32 v124, v108, v124
	v_fmamk_f32 v108, v109, 0xbdd2d3e8, v213
	v_mul_f32_e32 v108, v157, v108
	v_exp_f32_e32 v108, v108
	s_nop 0
	v_add_f32_e32 v108, 1.0, v108
	v_rcp_f32_e32 v108, v108
	s_nop 0
	v_mul_f32_e32 v108, v157, v108
	v_mul_f32_e32 v110, v108, v110
	v_pk_mul_f32 v[108:109], v[154:155], v[154:155]
	s_nop 0
	v_fmamk_f32 v108, v108, 0xbdd2d3e8, v213
	v_mul_f32_e32 v108, v154, v108
	v_exp_f32_e32 v108, v108
	s_nop 0
	v_add_f32_e32 v108, 1.0, v108
	v_rcp_f32_e32 v108, v108
	s_nop 0
	v_mul_f32_e32 v108, v154, v108
	v_mul_f32_e32 v125, v108, v125
	v_fmamk_f32 v108, v109, 0xbdd2d3e8, v213
	v_mul_f32_e32 v108, v155, v108
	v_exp_f32_e32 v108, v108
	s_nop 0
	v_add_f32_e32 v108, 1.0, v108
	v_rcp_f32_e32 v108, v108
	s_nop 0
	v_mul_f32_e32 v108, v155, v108
	v_mul_f32_e32 v111, v108, v111
	v_cvt_pk_bf16_f32 v108, v112, v113
	v_cvt_pk_bf16_f32 v109, v114, v115
	v_cvt_pk_bf16_f32 v110, v124, v110
	v_cvt_pk_bf16_f32 v111, v125, v111
	global_store_dwordx4 v[122:123], v[108:111], off
	s_waitcnt vmcnt(3)
	v_lshlrev_b32_e32 v112, 16, v106
	v_and_b32_e32 v106, 0xffff0000, v106
	v_lshlrev_b32_e32 v108, 16, v104
	v_and_b32_e32 v109, 0xffff0000, v104
	v_lshlrev_b32_e32 v110, 16, v105
	v_and_b32_e32 v111, 0xffff0000, v105
	v_pk_mul_f32 v[104:105], v[138:139], v[138:139]
	v_lshlrev_b32_e32 v113, 16, v107
	v_fmamk_f32 v104, v104, 0xbdd2d3e8, v213
	v_mul_f32_e32 v104, v138, v104
	v_exp_f32_e32 v104, v104
	v_and_b32_e32 v107, 0xffff0000, v107
	v_add_f32_e32 v104, 1.0, v104
	v_rcp_f32_e32 v104, v104
	s_nop 0
	v_mul_f32_e32 v104, v138, v104
	v_mul_f32_e32 v108, v104, v108
	v_fmamk_f32 v104, v105, 0xbdd2d3e8, v213
	v_mul_f32_e32 v104, v139, v104
	v_exp_f32_e32 v104, v104
	s_nop 0
	v_add_f32_e32 v104, 1.0, v104
	v_rcp_f32_e32 v104, v104
	s_nop 0
	v_mul_f32_e32 v104, v139, v104
	v_mul_f32_e32 v109, v104, v109
	v_pk_mul_f32 v[104:105], v[134:135], v[134:135]
	s_nop 0
	v_fmamk_f32 v104, v104, 0xbdd2d3e8, v213
	v_mul_f32_e32 v104, v134, v104
	v_exp_f32_e32 v104, v104
	s_nop 0
	v_add_f32_e32 v104, 1.0, v104
	v_rcp_f32_e32 v104, v104
	s_nop 0
	v_mul_f32_e32 v104, v134, v104
	v_mul_f32_e32 v110, v104, v110
	v_fmamk_f32 v104, v105, 0xbdd2d3e8, v213
	v_mul_f32_e32 v104, v135, v104
	v_exp_f32_e32 v104, v104
	s_nop 0
	v_add_f32_e32 v104, 1.0, v104
	v_rcp_f32_e32 v104, v104
	s_nop 0
	v_mul_f32_e32 v104, v135, v104
	v_mul_f32_e32 v111, v104, v111
	v_pk_mul_f32 v[104:105], v[130:131], v[130:131]
	s_nop 0
	v_fmamk_f32 v104, v104, 0xbdd2d3e8, v213
	v_mul_f32_e32 v104, v130, v104
	v_exp_f32_e32 v104, v104
	s_nop 0
	v_add_f32_e32 v104, 1.0, v104
	v_rcp_f32_e32 v104, v104
	s_nop 0
	v_mul_f32_e32 v104, v130, v104
	v_mul_f32_e32 v112, v104, v112
	v_fmamk_f32 v104, v105, 0xbdd2d3e8, v213
	v_mul_f32_e32 v104, v131, v104
	v_exp_f32_e32 v104, v104
	s_nop 0
	v_add_f32_e32 v104, 1.0, v104
	v_rcp_f32_e32 v104, v104
	s_nop 0
	v_mul_f32_e32 v104, v131, v104
	v_mul_f32_e32 v106, v104, v106
	v_pk_mul_f32 v[104:105], v[126:127], v[126:127]
	s_nop 0
	v_fmamk_f32 v104, v104, 0xbdd2d3e8, v213
	v_mul_f32_e32 v104, v126, v104
	v_exp_f32_e32 v104, v104
	s_nop 0
	v_add_f32_e32 v104, 1.0, v104
	v_rcp_f32_e32 v104, v104
	s_nop 0
	v_mul_f32_e32 v104, v126, v104
	v_mul_f32_e32 v113, v104, v113
	v_fmamk_f32 v104, v105, 0xbdd2d3e8, v213
	v_mul_f32_e32 v104, v127, v104
	v_exp_f32_e32 v104, v104
	s_nop 0
	v_add_f32_e32 v104, 1.0, v104
	v_rcp_f32_e32 v104, v104
	s_nop 0
	v_mul_f32_e32 v104, v127, v104
	v_mul_f32_e32 v107, v104, v107
	v_cvt_pk_bf16_f32 v104, v108, v109
	v_cvt_pk_bf16_f32 v105, v110, v111
	v_cvt_pk_bf16_f32 v106, v112, v106
	v_cvt_pk_bf16_f32 v107, v113, v107
	global_store_dwordx4 v[120:121], v[104:107], off
	s_waitcnt vmcnt(3)
	v_lshlrev_b32_e32 v108, 16, v102
	v_and_b32_e32 v102, 0xffff0000, v102
	v_lshlrev_b32_e32 v104, 16, v100
	v_and_b32_e32 v105, 0xffff0000, v100
	v_lshlrev_b32_e32 v106, 16, v101
	v_and_b32_e32 v107, 0xffff0000, v101
	v_pk_mul_f32 v[100:101], v[152:153], v[152:153]
	v_lshlrev_b32_e32 v109, 16, v103
	v_fmamk_f32 v100, v100, 0xbdd2d3e8, v213
	v_mul_f32_e32 v100, v152, v100
	v_exp_f32_e32 v100, v100
	v_and_b32_e32 v103, 0xffff0000, v103
	v_add_f32_e32 v100, 1.0, v100
	v_rcp_f32_e32 v100, v100
	s_nop 0
	v_mul_f32_e32 v100, v152, v100
	v_mul_f32_e32 v104, v100, v104
	v_fmamk_f32 v100, v101, 0xbdd2d3e8, v213
	v_mul_f32_e32 v100, v153, v100
	v_exp_f32_e32 v100, v100
	s_nop 0
	v_add_f32_e32 v100, 1.0, v100
	v_rcp_f32_e32 v100, v100
	s_nop 0
	v_mul_f32_e32 v100, v153, v100
	v_mul_f32_e32 v105, v100, v105
	v_pk_mul_f32 v[100:101], v[136:137], v[136:137]
	s_nop 0
	v_fmamk_f32 v100, v100, 0xbdd2d3e8, v213
	v_mul_f32_e32 v100, v136, v100
	v_exp_f32_e32 v100, v100
	s_nop 0
	v_add_f32_e32 v100, 1.0, v100
	v_rcp_f32_e32 v100, v100
	s_nop 0
	v_mul_f32_e32 v100, v136, v100
	v_mul_f32_e32 v106, v100, v106
	v_fmamk_f32 v100, v101, 0xbdd2d3e8, v213
	v_mul_f32_e32 v100, v137, v100
	v_exp_f32_e32 v100, v100
	s_nop 0
	v_add_f32_e32 v100, 1.0, v100
	v_rcp_f32_e32 v100, v100
	s_nop 0
	v_mul_f32_e32 v100, v137, v100
	v_mul_f32_e32 v107, v100, v107
	v_pk_mul_f32 v[100:101], v[132:133], v[132:133]
	s_nop 0
	v_fmamk_f32 v100, v100, 0xbdd2d3e8, v213
	v_mul_f32_e32 v100, v132, v100
	v_exp_f32_e32 v100, v100
	s_nop 0
	v_add_f32_e32 v100, 1.0, v100
	v_rcp_f32_e32 v100, v100
	s_nop 0
	v_mul_f32_e32 v100, v132, v100
	v_mul_f32_e32 v108, v100, v108
	v_fmamk_f32 v100, v101, 0xbdd2d3e8, v213
	v_mul_f32_e32 v100, v133, v100
	v_exp_f32_e32 v100, v100
	s_nop 0
	v_add_f32_e32 v100, 1.0, v100
	v_rcp_f32_e32 v100, v100
	s_nop 0
	v_mul_f32_e32 v100, v133, v100
	v_mul_f32_e32 v102, v100, v102
	v_pk_mul_f32 v[100:101], v[128:129], v[128:129]
	s_nop 0
	v_fmamk_f32 v100, v100, 0xbdd2d3e8, v213
	v_mul_f32_e32 v100, v128, v100
	v_exp_f32_e32 v100, v100
	s_nop 0
	v_add_f32_e32 v100, 1.0, v100
	v_rcp_f32_e32 v100, v100
	s_nop 0
	v_mul_f32_e32 v100, v128, v100
	v_mul_f32_e32 v109, v100, v109
	v_fmamk_f32 v100, v101, 0xbdd2d3e8, v213
	v_mul_f32_e32 v100, v129, v100
	v_exp_f32_e32 v100, v100
	s_nop 0
	v_add_f32_e32 v100, 1.0, v100
	v_rcp_f32_e32 v100, v100
	s_nop 0
	v_mul_f32_e32 v100, v129, v100
	v_mul_f32_e32 v103, v100, v103
	v_cvt_pk_bf16_f32 v100, v104, v105
	v_cvt_pk_bf16_f32 v101, v106, v107
	v_cvt_pk_bf16_f32 v102, v108, v102
	v_cvt_pk_bf16_f32 v103, v109, v103
	global_store_dwordx4 v[118:119], v[100:103], off
	s_barrier
	s_cbranch_vccnz .LBB0_1326
	s_mul_hi_i32 s4, s90, 0x55555556
	s_lshr_b32 s5, s4, 31
	s_add_i32 s4, s4, s5
	s_mul_i32 s4, s4, 3
	s_sub_i32 s4, s90, s4
	s_mul_i32 s4, s4, 0x8400
	v_add_u32_e32 v100, s4, v170
	ds_write_b128 v100, v[80:83]
	ds_write_b128 v100, v[88:91] offset:8192
	ds_write_b128 v100, v[84:87] offset:16384
	ds_write_b128 v100, v[92:95] offset:24576
	s_and_saveexec_b64 s[4:5], s[42:43]
	s_cbranch_execz .LBB0_1325
	ds_write_b128 v100, v[96:99] offset:32768
	s_branch .LBB0_1325
